# GEMM3 epilogue: leftover vmcnt(0) drain before the row scales removed (values were loaded in the tile header)
# baseline (speedup 1.0000x reference)
; DI unsigned cvt_pk_bf16(float lo, float hi) { f32x2 v = {lo, hi}; bf16v2 b = __builtin_convertvector(v, bf16v2); return __builtin_bit_cast(unsigned, b); }
;     DI void operator()(const f32x4 (&acc)[2][2][4][2], const Unit& u, int wr, int wc, int fr, int fq) const {
;         const int row0 = u.pm * BM + wr * 64 + fr; const int col0 = u.pn * BM + wc * 32 + 8 * fq;
;         float rs[2][4];
; #pragma unroll
;         for (int ai = 0; ai < 2; ++ai)
; #pragma unroll
;             for (int m = 0; m < 4; ++m) rs[ai][m] = ssq ? __builtin_amdgcn_rsqf(ssq[row0 + ai * HALF + m * 16] * (1.0f / 4096.0f) + 1e-6f) : 1.0f;
; #pragma unroll
;         for (int ai = 0; ai < 2; ++ai)
; #pragma unroll
;             for (int m = 0; m < 4; ++m) { bf16_t* rowp = O + (size_t)(row0 + ai * HALF + m * 16) * ldc + col0; const float s = rs[ai][m];
; #pragma unroll
;                 for (int bj = 0; bj < 2; ++bj) { const f32x4 v0 = acc[ai][bj][m][0] * s, v1 = acc[ai][bj][m][1] * s;
;                     u32x4 w; w.x = cvt_pk_bf16(v0[0], v0[1]); w.y = cvt_pk_bf16(v0[2], v0[3]); w.z = cvt_pk_bf16(v1[0], v1[1]); w.w = cvt_pk_bf16(v1[2], v1[3]);
;                     *(u32x4*)(rowp + bj * HALF) = w; } }
.LBB0_528:
	v_lshl_add_u32 v148, s20, 8, v157
	v_ashrrev_i32_e32 v149, 31, v148
	v_lshl_add_u64 v[146:147], v[148:149], 2, s[8:9]
	v_mov_b32_e32 v149, v236
	v_mov_b32_e32 v150, v237
	v_mov_b32_e32 v167, v238
	v_mov_b32_e32 v174, v239
	v_mov_b32_e32 v175, v240
	v_mov_b32_e32 v176, v241
	v_mov_b32_e32 v177, v242
	v_mov_b32_e32 v178, v243
	v_readlane_b32 s22, v253, 28
	v_lshl_or_b32 v164, s41, 8, v159
	v_readlane_b32 s23, v253, 29
	v_ashrrev_i32_e32 v165, 31, v164
	v_add_u32_e32 v179, 0x80, v148
	v_mov_b64_e32 v[146:147], s[22:23]
	v_mad_i64_i32 v[168:169], s[22:23], v148, s40, v[146:147]
	v_or_b32_e32 v170, 16, v148
	v_or_b32_e32 v172, 32, v148
	v_lshlrev_b64 v[164:165], 1, v[164:165]
	v_mad_i64_i32 v[170:171], s[22:23], v170, s40, v[146:147]
	v_mad_i64_i32 v[172:173], s[22:23], v172, s40, v[146:147]
	v_lshl_add_u64 v[168:169], v[168:169], 0, v[164:165]
	v_lshl_add_u64 v[170:171], v[170:171], 0, v[164:165]
	v_lshl_add_u64 v[172:173], v[172:173], 0, v[164:165]
	v_add_u32_e32 v181, 0xb0, v148
	s_andn2_b64 vcc, exec, s[0:1]
	s_mov_b64 s[0:1], -1
	s_nop 0
	v_fmamk_f32 v149, v149, 0x39800000, v163
	v_fmamk_f32 v150, v150, 0x39800000, v163
	v_fmamk_f32 v167, v167, 0x39800000, v163
	v_fmamk_f32 v180, v174, 0x39800000, v163
	v_rsq_f32_e32 v174, v149
	v_fmamk_f32 v183, v176, 0x39800000, v163
	v_rsq_f32_e32 v176, v150
	v_fmamk_f32 v185, v178, 0x39800000, v163
	v_rsq_f32_e32 v178, v167
	v_fmamk_f32 v175, v175, 0x39800000, v163
	v_fmamk_f32 v177, v177, 0x39800000, v163
	v_pk_mul_f32 v[128:129], v[128:129], v[174:175] op_sel_hi:[1,0]
	v_pk_mul_f32 v[126:127], v[126:127], v[174:175] op_sel_hi:[1,0]
	v_pk_mul_f32 v[124:125], v[124:125], v[174:175] op_sel_hi:[1,0]
	v_pk_mul_f32 v[122:123], v[122:123], v[174:175] op_sel_hi:[1,0]
	v_rsq_f32_e32 v182, v175
	v_rsq_f32_e32 v186, v177
	v_pk_mul_f32 v[108:109], v[108:109], v[174:175] op_sel_hi:[1,0]
	v_pk_mul_f32 v[106:107], v[106:107], v[174:175] op_sel_hi:[1,0]
	v_pk_mul_f32 v[104:105], v[104:105], v[174:175] op_sel_hi:[1,0]
	v_pk_mul_f32 v[102:103], v[102:103], v[174:175] op_sel_hi:[1,0]
	v_pk_mul_f32 v[120:121], v[120:121], v[176:177] op_sel_hi:[1,0]
	v_pk_mul_f32 v[118:119], v[118:119], v[176:177] op_sel_hi:[1,0]
	v_pk_mul_f32 v[116:117], v[116:117], v[176:177] op_sel_hi:[1,0]
	v_pk_mul_f32 v[114:115], v[114:115], v[176:177] op_sel_hi:[1,0]
	v_pk_mul_f32 v[174:175], v[96:97], v[176:177] op_sel_hi:[1,0]
	v_pk_mul_f32 v[188:189], v[94:95], v[176:177] op_sel_hi:[1,0]
	v_pk_mul_f32 v[190:191], v[92:93], v[176:177] op_sel_hi:[1,0]
	v_pk_mul_f32 v[176:177], v[90:91], v[176:177] op_sel_hi:[1,0]
	v_pk_mul_f32 v[112:113], v[112:113], v[178:179] op_sel_hi:[1,0]
	v_pk_mul_f32 v[110:111], v[110:111], v[178:179] op_sel_hi:[1,0]
	v_pk_mul_f32 v[192:193], v[100:101], v[178:179] op_sel_hi:[1,0]
	v_pk_mul_f32 v[194:195], v[98:99], v[178:179] op_sel_hi:[1,0]
	v_pk_mul_f32 v[196:197], v[88:89], v[178:179] op_sel_hi:[1,0]
	v_pk_mul_f32 v[198:199], v[86:87], v[178:179] op_sel_hi:[1,0]
	v_cvt_pk_bf16_f32 v86, v126, v127
	v_cvt_pk_bf16_f32 v87, v128, v129
	v_cvt_pk_bf16_f32 v88, v122, v123
	v_cvt_pk_bf16_f32 v89, v124, v125
	v_rsq_f32_e32 v180, v180
	v_cvt_pk_bf16_f32 v90, v106, v107
	v_cvt_pk_bf16_f32 v91, v108, v109
	v_cvt_pk_bf16_f32 v92, v102, v103
	v_cvt_pk_bf16_f32 v93, v104, v105
	v_cvt_pk_bf16_f32 v94, v118, v119
	v_cvt_pk_bf16_f32 v95, v120, v121
	v_cvt_pk_bf16_f32 v96, v114, v115
	v_cvt_pk_bf16_f32 v97, v116, v117
	v_cvt_pk_bf16_f32 v98, v188, v189
	v_cvt_pk_bf16_f32 v99, v174, v175
	v_cvt_pk_bf16_f32 v100, v176, v177
	v_cvt_pk_bf16_f32 v101, v190, v191
	v_cvt_pk_bf16_f32 v102, v110, v111
	v_cvt_pk_bf16_f32 v103, v112, v113
	v_cvt_pk_bf16_f32 v104, v194, v195
	v_cvt_pk_bf16_f32 v105, v192, v193
	global_store_dwordx4 v[168:169], v[86:89], off
	global_store_dwordx4 v[168:169], v[90:93], off offset:256
	global_store_dwordx4 v[170:171], v[94:97], off
	global_store_dwordx4 v[170:171], v[98:101], off offset:256
	global_store_dwordx4 v[172:173], v[102:105], off
	v_pk_mul_f32 v[86:87], v[76:77], v[178:179] op_sel_hi:[1,0]
	v_pk_mul_f32 v[76:77], v[74:75], v[178:179] op_sel_hi:[1,0]
	v_cvt_pk_bf16_f32 v74, v198, v199
	v_cvt_pk_bf16_f32 v75, v196, v197
	v_cvt_pk_bf16_f32 v76, v76, v77
	v_cvt_pk_bf16_f32 v77, v86, v87
	global_store_dwordx4 v[172:173], v[74:77], off offset:256
	v_pk_mul_f32 v[80:81], v[80:81], v[180:181] op_sel_hi:[1,0]
	v_pk_mul_f32 v[78:79], v[78:79], v[180:181] op_sel_hi:[1,0]
	v_or_b32_e32 v74, 48, v148
	v_mad_i64_i32 v[74:75], s[22:23], v74, s40, v[146:147]
	v_lshl_add_u64 v[86:87], v[74:75], 0, v[164:165]
	v_pk_mul_f32 v[76:77], v[84:85], v[180:181] op_sel_hi:[1,0]
	v_pk_mul_f32 v[74:75], v[82:83], v[180:181] op_sel_hi:[1,0]
; DI unsigned cvt_pk_bf16(float lo, float hi) { f32x2 v = {lo, hi}; bf16v2 b = __builtin_convertvector(v, bf16v2); return __builtin_bit_cast(unsigned, b); }
; #define PG8_BAR __builtin_amdgcn_s_barrier()
;     DI void operator()(const f32x4 (&acc)[2][2][4][2], const Unit& u, int wr, int wc, int fr, int fq) const {
;     ...
;             for (int m = 0; m < 4; ++m) { bf16_t* rowp = O + (size_t)(row0 + ai * HALF + m * 16) * ldc + col0; const float s = rs[ai][m];
; #pragma unroll
;                 for (int bj = 0; bj < 2; ++bj) { const f32x4 v0 = acc[ai][bj][m][0] * s, v1 = acc[ai][bj][m][1] * s;
;                     u32x4 w; w.x = cvt_pk_bf16(v0[0], v0[1]); w.y = cvt_pk_bf16(v0[2], v0[3]); w.z = cvt_pk_bf16(v1[0], v1[1]); w.w = cvt_pk_bf16(v1[2], v1[3]);
;                     *(u32x4*)(rowp + bj * HALF) = w; } }
; template <class Epi, class Sched, bool ALIGN_EPI = false, bool SP2 = false>
; __device__ __forceinline__ void gemm_phase(PG8_LAS unsigned char* lds, const Gemm g, const Sched& S, const Epi& E) {
;     ...
;         if constexpr (ALIGN_EPI) { if (wr == 1) PG8_BAR; }
	v_pk_mul_f32 v[72:73], v[72:73], v[180:181] op_sel_hi:[1,0]
	v_cvt_pk_bf16_f32 v74, v74, v75
	v_cvt_pk_bf16_f32 v75, v76, v77
	v_cvt_pk_bf16_f32 v76, v78, v79
	v_cvt_pk_bf16_f32 v77, v80, v81
	global_store_dwordx4 v[86:87], v[74:77], off
	v_pk_mul_f32 v[70:71], v[70:71], v[180:181] op_sel_hi:[1,0]
	v_pk_mul_f32 v[64:65], v[64:65], v[182:183] op_sel_hi:[1,0]
	v_pk_mul_f32 v[74:75], v[68:69], v[180:181] op_sel_hi:[1,0]
	v_pk_mul_f32 v[68:69], v[66:67], v[180:181] op_sel_hi:[1,0]
	v_cvt_pk_bf16_f32 v66, v70, v71
	v_cvt_pk_bf16_f32 v67, v72, v73
	v_cvt_pk_bf16_f32 v68, v68, v69
	v_cvt_pk_bf16_f32 v69, v74, v75
	global_store_dwordx4 v[86:87], v[66:69], off offset:256
	v_pk_mul_f32 v[62:63], v[62:63], v[182:183] op_sel_hi:[1,0]
	v_rsq_f32_e32 v184, v183
	v_mad_i64_i32 v[66:67], s[22:23], v179, s40, v[146:147]
	v_pk_mul_f32 v[68:69], v[60:61], v[182:183] op_sel_hi:[1,0]
	v_pk_mul_f32 v[60:61], v[58:59], v[182:183] op_sel_hi:[1,0]
	v_lshl_add_u64 v[66:67], v[66:67], 0, v[164:165]
	v_cvt_pk_bf16_f32 v58, v62, v63
	v_cvt_pk_bf16_f32 v59, v64, v65
	v_cvt_pk_bf16_f32 v60, v60, v61
	v_cvt_pk_bf16_f32 v61, v68, v69
	global_store_dwordx4 v[66:67], v[58:61], off
	v_pk_mul_f32 v[52:53], v[52:53], v[182:183] op_sel_hi:[1,0]
	v_pk_mul_f32 v[50:51], v[50:51], v[182:183] op_sel_hi:[1,0]
	v_pk_mul_f32 v[58:59], v[44:45], v[182:183] op_sel_hi:[1,0]
	v_pk_mul_f32 v[44:45], v[42:43], v[182:183] op_sel_hi:[1,0]
	v_cvt_pk_bf16_f32 v42, v50, v51
	v_cvt_pk_bf16_f32 v43, v52, v53
	v_cvt_pk_bf16_f32 v44, v44, v45
	v_cvt_pk_bf16_f32 v45, v58, v59
	global_store_dwordx4 v[66:67], v[42:45], off offset:256
	v_pk_mul_f32 v[48:49], v[48:49], v[184:185] op_sel_hi:[1,0]
	v_pk_mul_f32 v[46:47], v[46:47], v[184:185] op_sel_hi:[1,0]
	v_add_u32_e32 v42, 0x90, v148
	v_mad_i64_i32 v[42:43], s[22:23], v42, s40, v[146:147]
	v_lshl_add_u64 v[50:51], v[42:43], 0, v[164:165]
	v_pk_mul_f32 v[44:45], v[56:57], v[184:185] op_sel_hi:[1,0]
	v_pk_mul_f32 v[42:43], v[54:55], v[184:185] op_sel_hi:[1,0]
	v_pk_mul_f32 v[36:37], v[36:37], v[184:185] op_sel_hi:[1,0]
	v_cvt_pk_bf16_f32 v42, v42, v43
	v_cvt_pk_bf16_f32 v43, v44, v45
	v_cvt_pk_bf16_f32 v44, v46, v47
	v_cvt_pk_bf16_f32 v45, v48, v49
	global_store_dwordx4 v[50:51], v[42:45], off
	v_pk_mul_f32 v[34:35], v[34:35], v[184:185] op_sel_hi:[1,0]
	v_pk_mul_f32 v[32:33], v[32:33], v[186:187] op_sel_hi:[1,0]
	v_pk_mul_f32 v[42:43], v[28:29], v[184:185] op_sel_hi:[1,0]
	v_pk_mul_f32 v[28:29], v[26:27], v[184:185] op_sel_hi:[1,0]
	v_cvt_pk_bf16_f32 v26, v34, v35
	v_cvt_pk_bf16_f32 v27, v36, v37
	v_cvt_pk_bf16_f32 v28, v28, v29
	v_cvt_pk_bf16_f32 v29, v42, v43
	global_store_dwordx4 v[50:51], v[26:29], off offset:256
	v_pk_mul_f32 v[30:31], v[30:31], v[186:187] op_sel_hi:[1,0]
	v_rsq_f32_e32 v150, v185
	v_add_u32_e32 v26, 0xa0, v148
	v_mad_i64_i32 v[26:27], s[22:23], v26, s40, v[146:147]
	v_lshl_add_u64 v[34:35], v[26:27], 0, v[164:165]
	v_pk_mul_f32 v[28:29], v[40:41], v[186:187] op_sel_hi:[1,0]
	v_pk_mul_f32 v[26:27], v[38:39], v[186:187] op_sel_hi:[1,0]
	v_pk_mul_f32 v[20:21], v[20:21], v[186:187] op_sel_hi:[1,0]
	v_cvt_pk_bf16_f32 v26, v26, v27
	v_cvt_pk_bf16_f32 v27, v28, v29
	v_cvt_pk_bf16_f32 v28, v30, v31
	v_cvt_pk_bf16_f32 v29, v32, v33
	global_store_dwordx4 v[34:35], v[26:29], off
	v_pk_mul_f32 v[18:19], v[18:19], v[186:187] op_sel_hi:[1,0]
	v_pk_mul_f32 v[16:17], v[16:17], v[150:151] op_sel_hi:[1,0]
	v_pk_mul_f32 v[26:27], v[12:13], v[186:187] op_sel_hi:[1,0]
	v_pk_mul_f32 v[12:13], v[10:11], v[186:187] op_sel_hi:[1,0]
	v_cvt_pk_bf16_f32 v10, v18, v19
	v_cvt_pk_bf16_f32 v11, v20, v21
	v_cvt_pk_bf16_f32 v12, v12, v13
	v_cvt_pk_bf16_f32 v13, v26, v27
	global_store_dwordx4 v[34:35], v[10:13], off offset:256
	v_pk_mul_f32 v[14:15], v[14:15], v[150:151] op_sel_hi:[1,0]
	v_pk_mul_f32 v[8:9], v[8:9], v[150:151] op_sel_hi:[1,0]
	v_mad_i64_i32 v[10:11], s[22:23], v181, s40, v[146:147]
	v_lshl_add_u64 v[18:19], v[10:11], 0, v[164:165]
	v_pk_mul_f32 v[12:13], v[24:25], v[150:151] op_sel_hi:[1,0]
	v_pk_mul_f32 v[10:11], v[22:23], v[150:151] op_sel_hi:[1,0]
	v_pk_mul_f32 v[6:7], v[6:7], v[150:151] op_sel_hi:[1,0]
	v_cvt_pk_bf16_f32 v10, v10, v11
	v_cvt_pk_bf16_f32 v11, v12, v13
	v_cvt_pk_bf16_f32 v12, v14, v15
	v_cvt_pk_bf16_f32 v13, v16, v17
	global_store_dwordx4 v[18:19], v[10:13], off
	s_nop 1
	v_pk_mul_f32 v[10:11], v[4:5], v[150:151] op_sel_hi:[1,0]
	v_pk_mul_f32 v[4:5], v[2:3], v[150:151] op_sel_hi:[1,0]
	v_cvt_pk_bf16_f32 v2, v6, v7
	v_cvt_pk_bf16_f32 v3, v8, v9
	v_cvt_pk_bf16_f32 v4, v4, v5
	v_cvt_pk_bf16_f32 v5, v10, v11
	global_store_dwordx4 v[18:19], v[2:5], off offset:256
	s_cmp_eq_u64 s[10:11], 0
	s_cbranch_scc1 .Lg3_noalign
	s_barrier
